# panel-counter waits (FFN-out / W_out): agent acquire issued before the wait loop instead of after it
# speedup vs baseline: 1.0030x; 1.0030x over previous
.LBB0_997:
	s_or_b64 exec, exec, s[6:7]
	buffer_inv sc1
	s_memrealtime s[6:7]
	v_mov_b32_e32 v1, 0
	v_mov_b64_e32 v[2:3], 0x4c4b40
	s_branch .LBB0_999

.LBB0_1001:
	s_waitcnt lgkmcnt(0)
	s_waitcnt vmcnt(0)

.LBB0_5941:
	s_or_b64 exec, exec, s[2:3]
	buffer_inv sc1
	s_memrealtime s[2:3]
	v_mov_b32_e32 v1, 0
	v_mov_b64_e32 v[2:3], 0x4c4b40
	s_branch .LBB0_5943
